# compress MLP K-split over 8 waves with LDS reduction; compressed K/V lane-linear layout; top-k rounds hand-written (interleaved chains, dpp max, single store)
# speedup vs baseline: 1.1117x; 1.0201x over previous
.LBB0_390:
	v_mul_lo_u32 v0, v143, s46
	v_add_u32_e32 v89, s5, v0
	s_cmpk_lg_i32 s46, 0x100
	s_cbranch_scc1 .Lcmpr_orig
	s_mov_b64 s[12:13], exec
	s_lshr_b32 s2, s5, 7
	s_lshr_b32 s19, s5, 6
	s_and_b32 s19, s19, 1
	s_mov_b32 s18, 0x1cd00000
	s_mov_b32 s0, 0x1d100000
	s_cmp_eq_u32 s2, 0
	s_cselect_b32 s18, s18, s0
	s_lshl_b32 s0, s19, 7
	s_add_i32 s18, s18, s0
	s_add_u32 s0, s26, s18
	s_addc_u32 s1, s27, 0
	s_lshl_b32 s18, s2, 19
	s_add_i32 s18, s18, 0x2800000
	s_add_u32 s8, s26, s18
	s_addc_u32 s9, s27, 0
	s_add_u32 s10, s8, 0x10000
	s_addc_u32 s11, s9, 0
	s_add_u32 s14, s10, 0x10000
	s_addc_u32 s15, s11, 0
	s_add_u32 s16, s14, 0x10000
	s_addc_u32 s17, s15, 0
	v_readfirstlane_b32 s18, v143
	s_lshl_b32 s18, s18, 10
	s_add_u32 s0, s0, s18
	s_addc_u32 s1, s1, 0
	s_lshr_b32 s18, s18, 1
	s_add_u32 s8, s8, s18
	s_addc_u32 s9, s9, 0
	s_add_u32 s10, s10, s18
	s_addc_u32 s11, s11, 0
	s_add_u32 s14, s14, s18
	s_addc_u32 s15, s15, 0
	s_add_u32 s16, s16, s18
	s_addc_u32 s17, s17, 0
	v_and_b32_e32 v80, 15, v208
	v_bfe_u32 v86, v208, 4, 2
	s_and_b32 s18, s5, 63
	s_lshl_b32 s18, s18, 4
	v_add_u32_e32 v64, s18, v80
	v_lshlrev_b32_e32 v64, 4, v64
	v_min_u32_e32 v64, 0x3fe0, v64
	v_lshlrev_b32_e32 v64, 8, v64
	v_lshl_add_u32 v64, v86, 4, v64
	v_lshlrev_b32_e32 v78, 12, v80
	v_lshl_add_u32 v78, v86, 4, v78
	v_add_u32_e32 v79, 0x40000, v78
	v_mov_b32_e32 v0, 0
	v_mov_b32_e32 v1, 0
	v_mov_b32_e32 v2, 0
	v_mov_b32_e32 v3, 0
	v_mov_b32_e32 v4, 0
	v_mov_b32_e32 v5, 0
	v_mov_b32_e32 v6, 0
	v_mov_b32_e32 v7, 0
	v_mov_b32_e32 v8, 0
	v_mov_b32_e32 v9, 0
	v_mov_b32_e32 v10, 0
	v_mov_b32_e32 v11, 0
	v_mov_b32_e32 v12, 0
	v_mov_b32_e32 v13, 0
	v_mov_b32_e32 v14, 0
	v_mov_b32_e32 v15, 0
	v_mov_b32_e32 v16, 0
	v_mov_b32_e32 v17, 0
	v_mov_b32_e32 v18, 0
	v_mov_b32_e32 v19, 0
	v_mov_b32_e32 v20, 0
	v_mov_b32_e32 v21, 0
	v_mov_b32_e32 v22, 0
	v_mov_b32_e32 v23, 0
	v_mov_b32_e32 v24, 0
	v_mov_b32_e32 v25, 0
	v_mov_b32_e32 v26, 0
	v_mov_b32_e32 v27, 0
	v_mov_b32_e32 v28, 0
	v_mov_b32_e32 v29, 0
	v_mov_b32_e32 v30, 0
	v_mov_b32_e32 v31, 0
	global_load_dwordx4 v[32:35], v64, s[0:1]
	global_load_dwordx4 v[40:43], v78, s[8:9] offset:0
	global_load_dwordx4 v[44:47], v78, s[10:11] offset:0
	global_load_dwordx4 v[48:51], v78, s[14:15] offset:0
	global_load_dwordx4 v[52:55], v78, s[16:17] offset:0
	global_load_dwordx4 v[56:59], v79, s[8:9] offset:0
	global_load_dwordx4 v[60:63], v79, s[10:11] offset:0
	global_load_dwordx4 v[66:69], v79, s[14:15] offset:0
	global_load_dwordx4 v[70:73], v79, s[16:17] offset:0
	s_mov_b32 s18, 4
.Lcmpr_loop:
	global_load_dwordx4 v[36:39], v64, s[0:1] offset:64
	s_waitcnt vmcnt(8)
	v_mfma_f32_16x16x32_bf16 v[0:3], v[40:43], v[32:35], v[0:3]
	global_load_dwordx4 v[40:43], v78, s[8:9] offset:64
	s_waitcnt vmcnt(8)
	v_mfma_f32_16x16x32_bf16 v[4:7], v[44:47], v[32:35], v[4:7]
	global_load_dwordx4 v[44:47], v78, s[10:11] offset:64
	s_waitcnt vmcnt(8)
	v_mfma_f32_16x16x32_bf16 v[8:11], v[48:51], v[32:35], v[8:11]
	global_load_dwordx4 v[48:51], v78, s[14:15] offset:64
	s_waitcnt vmcnt(8)
	v_mfma_f32_16x16x32_bf16 v[12:15], v[52:55], v[32:35], v[12:15]
	global_load_dwordx4 v[52:55], v78, s[16:17] offset:64
	s_waitcnt vmcnt(8)
	v_mfma_f32_16x16x32_bf16 v[16:19], v[56:59], v[32:35], v[16:19]
	global_load_dwordx4 v[56:59], v79, s[8:9] offset:64
	s_waitcnt vmcnt(8)
	v_mfma_f32_16x16x32_bf16 v[20:23], v[60:63], v[32:35], v[20:23]
	global_load_dwordx4 v[60:63], v79, s[10:11] offset:64
	s_waitcnt vmcnt(8)
	v_mfma_f32_16x16x32_bf16 v[24:27], v[66:69], v[32:35], v[24:27]
	global_load_dwordx4 v[66:69], v79, s[14:15] offset:64
	s_waitcnt vmcnt(8)
	v_mfma_f32_16x16x32_bf16 v[28:31], v[70:73], v[32:35], v[28:31]
	global_load_dwordx4 v[70:73], v79, s[16:17] offset:64
	global_load_dwordx4 v[32:35], v64, s[0:1] offset:256
	s_waitcnt vmcnt(8)
	v_mfma_f32_16x16x32_bf16 v[0:3], v[40:43], v[36:39], v[0:3]
	global_load_dwordx4 v[40:43], v78, s[8:9] offset:128
	s_waitcnt vmcnt(8)
	v_mfma_f32_16x16x32_bf16 v[4:7], v[44:47], v[36:39], v[4:7]
	global_load_dwordx4 v[44:47], v78, s[10:11] offset:128
	s_waitcnt vmcnt(8)
	v_mfma_f32_16x16x32_bf16 v[8:11], v[48:51], v[36:39], v[8:11]
	global_load_dwordx4 v[48:51], v78, s[14:15] offset:128
	s_waitcnt vmcnt(8)
	v_mfma_f32_16x16x32_bf16 v[12:15], v[52:55], v[36:39], v[12:15]
	global_load_dwordx4 v[52:55], v78, s[16:17] offset:128
	s_waitcnt vmcnt(8)
	v_mfma_f32_16x16x32_bf16 v[16:19], v[56:59], v[36:39], v[16:19]
	global_load_dwordx4 v[56:59], v79, s[8:9] offset:128
	s_waitcnt vmcnt(8)
	v_mfma_f32_16x16x32_bf16 v[20:23], v[60:63], v[36:39], v[20:23]
	global_load_dwordx4 v[60:63], v79, s[10:11] offset:128
	s_waitcnt vmcnt(8)
	v_mfma_f32_16x16x32_bf16 v[24:27], v[66:69], v[36:39], v[24:27]
	global_load_dwordx4 v[66:69], v79, s[14:15] offset:128
	s_waitcnt vmcnt(8)
	v_mfma_f32_16x16x32_bf16 v[28:31], v[70:73], v[36:39], v[28:31]
	global_load_dwordx4 v[70:73], v79, s[16:17] offset:128
	s_add_u32 s0, s0, 0x100
	s_addc_u32 s1, s1, 0
	s_add_u32 s8, s8, 0x80
	s_addc_u32 s9, s9, 0
	s_add_u32 s10, s10, 0x80
	s_addc_u32 s11, s11, 0
	s_add_u32 s14, s14, 0x80
	s_addc_u32 s15, s15, 0
	s_add_u32 s16, s16, 0x80
	s_addc_u32 s17, s17, 0
	s_add_i32 s18, s18, -1
	s_cmp_lg_u32 s18, 0
	s_cbranch_scc1 .Lcmpr_loop
	s_waitcnt vmcnt(0)
	s_nop 7
	v_readfirstlane_b32 s18, v143
	s_lshl_b32 s0, s18, 13
	s_add_i32 s0, s0, 0x8000
	v_and_b32_e32 v87, 63, v208
	v_lshlrev_b32_e32 v87, 4, v87
	v_add_u32_e32 v64, s0, v87
	ds_write_b128 v64, v[0:3] offset:0
	ds_write_b128 v64, v[4:7] offset:1024
	ds_write_b128 v64, v[8:11] offset:2048
	ds_write_b128 v64, v[12:15] offset:3072
	ds_write_b128 v64, v[16:19] offset:4096
	ds_write_b128 v64, v[20:23] offset:5120
	ds_write_b128 v64, v[24:27] offset:6144
	ds_write_b128 v64, v[28:31] offset:7168
	s_waitcnt lgkmcnt(0)
	s_barrier
	s_cmp_lg_u32 s18, 0
	s_cbranch_scc1 .LBB0_399
	v_add_u32_e32 v64, 40960, v87
	ds_read_b128 v[40:43], v64 offset:0
	ds_read_b128 v[44:47], v64 offset:1024
	ds_read_b128 v[48:51], v64 offset:2048
	ds_read_b128 v[52:55], v64 offset:3072
	ds_read_b128 v[56:59], v64 offset:4096
	ds_read_b128 v[60:63], v64 offset:5120
	ds_read_b128 v[66:69], v64 offset:6144
	ds_read_b128 v[70:73], v64 offset:7168
	s_waitcnt lgkmcnt(0)
	v_pk_add_f32 v[0:1], v[0:1], v[40:41]
	v_pk_add_f32 v[2:3], v[2:3], v[42:43]
	v_pk_add_f32 v[4:5], v[4:5], v[44:45]
	v_pk_add_f32 v[6:7], v[6:7], v[46:47]
	v_pk_add_f32 v[8:9], v[8:9], v[48:49]
	v_pk_add_f32 v[10:11], v[10:11], v[50:51]
	v_pk_add_f32 v[12:13], v[12:13], v[52:53]
	v_pk_add_f32 v[14:15], v[14:15], v[54:55]
	v_pk_add_f32 v[16:17], v[16:17], v[56:57]
	v_pk_add_f32 v[18:19], v[18:19], v[58:59]
	v_pk_add_f32 v[20:21], v[20:21], v[60:61]
	v_pk_add_f32 v[22:23], v[22:23], v[62:63]
	v_pk_add_f32 v[24:25], v[24:25], v[66:67]
	v_pk_add_f32 v[26:27], v[26:27], v[68:69]
	v_pk_add_f32 v[28:29], v[28:29], v[70:71]
	v_pk_add_f32 v[30:31], v[30:31], v[72:73]
	v_add_u32_e32 v64, 49152, v87
	ds_read_b128 v[40:43], v64 offset:0
	ds_read_b128 v[44:47], v64 offset:1024
	ds_read_b128 v[48:51], v64 offset:2048
	ds_read_b128 v[52:55], v64 offset:3072
	ds_read_b128 v[56:59], v64 offset:4096
	ds_read_b128 v[60:63], v64 offset:5120
	ds_read_b128 v[66:69], v64 offset:6144
	ds_read_b128 v[70:73], v64 offset:7168
	s_waitcnt lgkmcnt(0)
	v_pk_add_f32 v[0:1], v[0:1], v[40:41]
	v_pk_add_f32 v[2:3], v[2:3], v[42:43]
	v_pk_add_f32 v[4:5], v[4:5], v[44:45]
	v_pk_add_f32 v[6:7], v[6:7], v[46:47]
	v_pk_add_f32 v[8:9], v[8:9], v[48:49]
	v_pk_add_f32 v[10:11], v[10:11], v[50:51]
	v_pk_add_f32 v[12:13], v[12:13], v[52:53]
	v_pk_add_f32 v[14:15], v[14:15], v[54:55]
	v_pk_add_f32 v[16:17], v[16:17], v[56:57]
	v_pk_add_f32 v[18:19], v[18:19], v[58:59]
	v_pk_add_f32 v[20:21], v[20:21], v[60:61]
	v_pk_add_f32 v[22:23], v[22:23], v[62:63]
	v_pk_add_f32 v[24:25], v[24:25], v[66:67]
	v_pk_add_f32 v[26:27], v[26:27], v[68:69]
	v_pk_add_f32 v[28:29], v[28:29], v[70:71]
	v_pk_add_f32 v[30:31], v[30:31], v[72:73]
	v_add_u32_e32 v64, 57344, v87
	ds_read_b128 v[40:43], v64 offset:0
	ds_read_b128 v[44:47], v64 offset:1024
	ds_read_b128 v[48:51], v64 offset:2048
	ds_read_b128 v[52:55], v64 offset:3072
	ds_read_b128 v[56:59], v64 offset:4096
	ds_read_b128 v[60:63], v64 offset:5120
	ds_read_b128 v[66:69], v64 offset:6144
	ds_read_b128 v[70:73], v64 offset:7168
	s_waitcnt lgkmcnt(0)
	v_pk_add_f32 v[0:1], v[0:1], v[40:41]
	v_pk_add_f32 v[2:3], v[2:3], v[42:43]
	v_pk_add_f32 v[4:5], v[4:5], v[44:45]
	v_pk_add_f32 v[6:7], v[6:7], v[46:47]
	v_pk_add_f32 v[8:9], v[8:9], v[48:49]
	v_pk_add_f32 v[10:11], v[10:11], v[50:51]
	v_pk_add_f32 v[12:13], v[12:13], v[52:53]
	v_pk_add_f32 v[14:15], v[14:15], v[54:55]
	v_pk_add_f32 v[16:17], v[16:17], v[56:57]
	v_pk_add_f32 v[18:19], v[18:19], v[58:59]
	v_pk_add_f32 v[20:21], v[20:21], v[60:61]
	v_pk_add_f32 v[22:23], v[22:23], v[62:63]
	v_pk_add_f32 v[24:25], v[24:25], v[66:67]
	v_pk_add_f32 v[26:27], v[26:27], v[68:69]
	v_pk_add_f32 v[28:29], v[28:29], v[70:71]
	v_pk_add_f32 v[30:31], v[30:31], v[72:73]
	v_add_u32_e32 v64, 65536, v87
	ds_read_b128 v[40:43], v64 offset:0
	ds_read_b128 v[44:47], v64 offset:1024
	ds_read_b128 v[48:51], v64 offset:2048
	ds_read_b128 v[52:55], v64 offset:3072
	ds_read_b128 v[56:59], v64 offset:4096
	ds_read_b128 v[60:63], v64 offset:5120
	ds_read_b128 v[66:69], v64 offset:6144
	ds_read_b128 v[70:73], v64 offset:7168
	s_waitcnt lgkmcnt(0)
	v_pk_add_f32 v[0:1], v[0:1], v[40:41]
	v_pk_add_f32 v[2:3], v[2:3], v[42:43]
	v_pk_add_f32 v[4:5], v[4:5], v[44:45]
	v_pk_add_f32 v[6:7], v[6:7], v[46:47]
	v_pk_add_f32 v[8:9], v[8:9], v[48:49]
	v_pk_add_f32 v[10:11], v[10:11], v[50:51]
	v_pk_add_f32 v[12:13], v[12:13], v[52:53]
	v_pk_add_f32 v[14:15], v[14:15], v[54:55]
	v_pk_add_f32 v[16:17], v[16:17], v[56:57]
	v_pk_add_f32 v[18:19], v[18:19], v[58:59]
	v_pk_add_f32 v[20:21], v[20:21], v[60:61]
	v_pk_add_f32 v[22:23], v[22:23], v[62:63]
	v_pk_add_f32 v[24:25], v[24:25], v[66:67]
	v_pk_add_f32 v[26:27], v[26:27], v[68:69]
	v_pk_add_f32 v[28:29], v[28:29], v[70:71]
	v_pk_add_f32 v[30:31], v[30:31], v[72:73]
	v_add_u32_e32 v64, 73728, v87
	ds_read_b128 v[40:43], v64 offset:0
	ds_read_b128 v[44:47], v64 offset:1024
	ds_read_b128 v[48:51], v64 offset:2048
	ds_read_b128 v[52:55], v64 offset:3072
	ds_read_b128 v[56:59], v64 offset:4096
	ds_read_b128 v[60:63], v64 offset:5120
	ds_read_b128 v[66:69], v64 offset:6144
	ds_read_b128 v[70:73], v64 offset:7168
	s_waitcnt lgkmcnt(0)
	v_pk_add_f32 v[0:1], v[0:1], v[40:41]
	v_pk_add_f32 v[2:3], v[2:3], v[42:43]
	v_pk_add_f32 v[4:5], v[4:5], v[44:45]
	v_pk_add_f32 v[6:7], v[6:7], v[46:47]
	v_pk_add_f32 v[8:9], v[8:9], v[48:49]
	v_pk_add_f32 v[10:11], v[10:11], v[50:51]
	v_pk_add_f32 v[12:13], v[12:13], v[52:53]
	v_pk_add_f32 v[14:15], v[14:15], v[54:55]
	v_pk_add_f32 v[16:17], v[16:17], v[56:57]
	v_pk_add_f32 v[18:19], v[18:19], v[58:59]
	v_pk_add_f32 v[20:21], v[20:21], v[60:61]
	v_pk_add_f32 v[22:23], v[22:23], v[62:63]
	v_pk_add_f32 v[24:25], v[24:25], v[66:67]
	v_pk_add_f32 v[26:27], v[26:27], v[68:69]
	v_pk_add_f32 v[28:29], v[28:29], v[70:71]
	v_pk_add_f32 v[30:31], v[30:31], v[72:73]
	v_add_u32_e32 v64, 81920, v87
	ds_read_b128 v[40:43], v64 offset:0
	ds_read_b128 v[44:47], v64 offset:1024
	ds_read_b128 v[48:51], v64 offset:2048
	ds_read_b128 v[52:55], v64 offset:3072
	ds_read_b128 v[56:59], v64 offset:4096
	ds_read_b128 v[60:63], v64 offset:5120
	ds_read_b128 v[66:69], v64 offset:6144
	ds_read_b128 v[70:73], v64 offset:7168
	s_waitcnt lgkmcnt(0)
	v_pk_add_f32 v[0:1], v[0:1], v[40:41]
	v_pk_add_f32 v[2:3], v[2:3], v[42:43]
	v_pk_add_f32 v[4:5], v[4:5], v[44:45]
	v_pk_add_f32 v[6:7], v[6:7], v[46:47]
	v_pk_add_f32 v[8:9], v[8:9], v[48:49]
	v_pk_add_f32 v[10:11], v[10:11], v[50:51]
	v_pk_add_f32 v[12:13], v[12:13], v[52:53]
	v_pk_add_f32 v[14:15], v[14:15], v[54:55]
	v_pk_add_f32 v[16:17], v[16:17], v[56:57]
	v_pk_add_f32 v[18:19], v[18:19], v[58:59]
	v_pk_add_f32 v[20:21], v[20:21], v[60:61]
	v_pk_add_f32 v[22:23], v[22:23], v[62:63]
	v_pk_add_f32 v[24:25], v[24:25], v[66:67]
	v_pk_add_f32 v[26:27], v[26:27], v[68:69]
	v_pk_add_f32 v[28:29], v[28:29], v[70:71]
	v_pk_add_f32 v[30:31], v[30:31], v[72:73]
	v_add_u32_e32 v64, 90112, v87
	ds_read_b128 v[40:43], v64 offset:0
	ds_read_b128 v[44:47], v64 offset:1024
	ds_read_b128 v[48:51], v64 offset:2048
	ds_read_b128 v[52:55], v64 offset:3072
	ds_read_b128 v[56:59], v64 offset:4096
	ds_read_b128 v[60:63], v64 offset:5120
	ds_read_b128 v[66:69], v64 offset:6144
	ds_read_b128 v[70:73], v64 offset:7168
	s_waitcnt lgkmcnt(0)
	v_pk_add_f32 v[0:1], v[0:1], v[40:41]
	v_pk_add_f32 v[2:3], v[2:3], v[42:43]
	v_pk_add_f32 v[4:5], v[4:5], v[44:45]
	v_pk_add_f32 v[6:7], v[6:7], v[46:47]
	v_pk_add_f32 v[8:9], v[8:9], v[48:49]
	v_pk_add_f32 v[10:11], v[10:11], v[50:51]
	v_pk_add_f32 v[12:13], v[12:13], v[52:53]
	v_pk_add_f32 v[14:15], v[14:15], v[54:55]
	v_pk_add_f32 v[16:17], v[16:17], v[56:57]
	v_pk_add_f32 v[18:19], v[18:19], v[58:59]
	v_pk_add_f32 v[20:21], v[20:21], v[60:61]
	v_pk_add_f32 v[22:23], v[22:23], v[62:63]
	v_pk_add_f32 v[24:25], v[24:25], v[66:67]
	v_pk_add_f32 v[26:27], v[26:27], v[68:69]
	v_pk_add_f32 v[28:29], v[28:29], v[70:71]
	v_pk_add_f32 v[30:31], v[30:31], v[72:73]
	s_lshl_b32 s18, s2, 9
	s_add_u32 s0, s26, s18
	s_addc_u32 s1, s27, 0
	v_lshlrev_b32_e32 v87, 4, v86
	global_load_dwordx4 v[40:43], v87, s[0:1] offset:0
	global_load_dwordx4 v[44:47], v87, s[0:1] offset:64
	global_load_dwordx4 v[48:51], v87, s[0:1] offset:128
	global_load_dwordx4 v[52:55], v87, s[0:1] offset:192
	global_load_dwordx4 v[56:59], v87, s[0:1] offset:256
	global_load_dwordx4 v[60:63], v87, s[0:1] offset:320
	global_load_dwordx4 v[66:69], v87, s[0:1] offset:384
	global_load_dwordx4 v[70:73], v87, s[0:1] offset:448
	s_lshl_b32 s18, s2, 14
	s_add_i32 s18, s18, 0x2900000
	s_add_u32 s8, s26, s18
	s_addc_u32 s9, s27, 0
	s_add_u32 s10, s8, 0x1000
	s_addc_u32 s11, s9, 0
	s_add_u32 s14, s10, 0x1000
	s_addc_u32 s15, s11, 0
	s_add_u32 s16, s14, 0x1000
	s_addc_u32 s17, s15, 0
	v_lshlrev_b32_e32 v78, 8, v80
	v_lshl_add_u32 v78, v86, 3, v78
	s_waitcnt vmcnt(0)
	s_nop 7
	v_add_f32_e32 v0, v0, v40
	v_mul_f32_e32 v40, v0, v0
	v_mul_f32_e32 v40, v40, v0
	v_fmamk_f32 v40, v40, 0x3d372713, v0
	v_mul_f32_e32 v40, 0x40135761, v40
	v_exp_f32_e32 v40, v40
	s_nop 0
	v_add_f32_e32 v40, 1.0, v40
	v_rcp_f32_e32 v40, v40
	s_nop 0
	v_fma_f32 v40, v40, -2.0, 2.0
	v_mul_f32_e32 v0, 0.5, v0
	v_mul_f32_e32 v0, v0, v40
	v_add_f32_e32 v1, v1, v41
	v_mul_f32_e32 v41, v1, v1
	v_mul_f32_e32 v41, v41, v1
	v_fmamk_f32 v41, v41, 0x3d372713, v1
	v_mul_f32_e32 v41, 0x40135761, v41
	v_exp_f32_e32 v41, v41
	s_nop 0
	v_add_f32_e32 v41, 1.0, v41
	v_rcp_f32_e32 v41, v41
	s_nop 0
	v_fma_f32 v41, v41, -2.0, 2.0
	v_mul_f32_e32 v1, 0.5, v1
	v_mul_f32_e32 v1, v1, v41
	v_add_f32_e32 v2, v2, v42
	v_mul_f32_e32 v42, v2, v2
	v_mul_f32_e32 v42, v42, v2
	v_fmamk_f32 v42, v42, 0x3d372713, v2
	v_mul_f32_e32 v42, 0x40135761, v42
	v_exp_f32_e32 v42, v42
	s_nop 0
	v_add_f32_e32 v42, 1.0, v42
	v_rcp_f32_e32 v42, v42
	s_nop 0
	v_fma_f32 v42, v42, -2.0, 2.0
	v_mul_f32_e32 v2, 0.5, v2
	v_mul_f32_e32 v2, v2, v42
	v_add_f32_e32 v3, v3, v43
	v_mul_f32_e32 v43, v3, v3
	v_mul_f32_e32 v43, v43, v3
	v_fmamk_f32 v43, v43, 0x3d372713, v3
	v_mul_f32_e32 v43, 0x40135761, v43
	v_exp_f32_e32 v43, v43
	s_nop 0
	v_add_f32_e32 v43, 1.0, v43
	v_rcp_f32_e32 v43, v43
	s_nop 0
	v_fma_f32 v43, v43, -2.0, 2.0
	v_mul_f32_e32 v3, 0.5, v3
	v_mul_f32_e32 v3, v3, v43
	v_add_f32_e32 v4, v4, v44
	v_mul_f32_e32 v44, v4, v4
	v_mul_f32_e32 v44, v44, v4
	v_fmamk_f32 v44, v44, 0x3d372713, v4
	v_mul_f32_e32 v44, 0x40135761, v44
	v_exp_f32_e32 v44, v44
	s_nop 0
	v_add_f32_e32 v44, 1.0, v44
	v_rcp_f32_e32 v44, v44
	s_nop 0
	v_fma_f32 v44, v44, -2.0, 2.0
	v_mul_f32_e32 v4, 0.5, v4
	v_mul_f32_e32 v4, v4, v44
	v_add_f32_e32 v5, v5, v45
	v_mul_f32_e32 v45, v5, v5
	v_mul_f32_e32 v45, v45, v5
	v_fmamk_f32 v45, v45, 0x3d372713, v5
	v_mul_f32_e32 v45, 0x40135761, v45
	v_exp_f32_e32 v45, v45
	s_nop 0
	v_add_f32_e32 v45, 1.0, v45
	v_rcp_f32_e32 v45, v45
	s_nop 0
	v_fma_f32 v45, v45, -2.0, 2.0
	v_mul_f32_e32 v5, 0.5, v5
	v_mul_f32_e32 v5, v5, v45
	v_add_f32_e32 v6, v6, v46
	v_mul_f32_e32 v46, v6, v6
	v_mul_f32_e32 v46, v46, v6
	v_fmamk_f32 v46, v46, 0x3d372713, v6
	v_mul_f32_e32 v46, 0x40135761, v46
	v_exp_f32_e32 v46, v46
	s_nop 0
	v_add_f32_e32 v46, 1.0, v46
	v_rcp_f32_e32 v46, v46
	s_nop 0
	v_fma_f32 v46, v46, -2.0, 2.0
	v_mul_f32_e32 v6, 0.5, v6
	v_mul_f32_e32 v6, v6, v46
	v_add_f32_e32 v7, v7, v47
	v_mul_f32_e32 v47, v7, v7
	v_mul_f32_e32 v47, v47, v7
	v_fmamk_f32 v47, v47, 0x3d372713, v7
	v_mul_f32_e32 v47, 0x40135761, v47
	v_exp_f32_e32 v47, v47
	s_nop 0
	v_add_f32_e32 v47, 1.0, v47
	v_rcp_f32_e32 v47, v47
	s_nop 0
	v_fma_f32 v47, v47, -2.0, 2.0
	v_mul_f32_e32 v7, 0.5, v7
	v_mul_f32_e32 v7, v7, v47
	v_add_f32_e32 v8, v8, v48
	v_mul_f32_e32 v48, v8, v8
	v_mul_f32_e32 v48, v48, v8
	v_fmamk_f32 v48, v48, 0x3d372713, v8
	v_mul_f32_e32 v48, 0x40135761, v48
	v_exp_f32_e32 v48, v48
	s_nop 0
	v_add_f32_e32 v48, 1.0, v48
	v_rcp_f32_e32 v48, v48
	s_nop 0
	v_fma_f32 v48, v48, -2.0, 2.0
	v_mul_f32_e32 v8, 0.5, v8
	v_mul_f32_e32 v8, v8, v48
	v_add_f32_e32 v9, v9, v49
	v_mul_f32_e32 v49, v9, v9
	v_mul_f32_e32 v49, v49, v9
	v_fmamk_f32 v49, v49, 0x3d372713, v9
	v_mul_f32_e32 v49, 0x40135761, v49
	v_exp_f32_e32 v49, v49
	s_nop 0
	v_add_f32_e32 v49, 1.0, v49
	v_rcp_f32_e32 v49, v49
	s_nop 0
	v_fma_f32 v49, v49, -2.0, 2.0
	v_mul_f32_e32 v9, 0.5, v9
	v_mul_f32_e32 v9, v9, v49
	v_add_f32_e32 v10, v10, v50
	v_mul_f32_e32 v50, v10, v10
	v_mul_f32_e32 v50, v50, v10
	v_fmamk_f32 v50, v50, 0x3d372713, v10
	v_mul_f32_e32 v50, 0x40135761, v50
	v_exp_f32_e32 v50, v50
	s_nop 0
	v_add_f32_e32 v50, 1.0, v50
	v_rcp_f32_e32 v50, v50
	s_nop 0
	v_fma_f32 v50, v50, -2.0, 2.0
	v_mul_f32_e32 v10, 0.5, v10
	v_mul_f32_e32 v10, v10, v50
	v_add_f32_e32 v11, v11, v51
	v_mul_f32_e32 v51, v11, v11
	v_mul_f32_e32 v51, v51, v11
	v_fmamk_f32 v51, v51, 0x3d372713, v11
	v_mul_f32_e32 v51, 0x40135761, v51
	v_exp_f32_e32 v51, v51
	s_nop 0
	v_add_f32_e32 v51, 1.0, v51
	v_rcp_f32_e32 v51, v51
	s_nop 0
	v_fma_f32 v51, v51, -2.0, 2.0
	v_mul_f32_e32 v11, 0.5, v11
	v_mul_f32_e32 v11, v11, v51
	v_add_f32_e32 v12, v12, v52
	v_mul_f32_e32 v52, v12, v12
	v_mul_f32_e32 v52, v52, v12
	v_fmamk_f32 v52, v52, 0x3d372713, v12
	v_mul_f32_e32 v52, 0x40135761, v52
	v_exp_f32_e32 v52, v52
	s_nop 0
	v_add_f32_e32 v52, 1.0, v52
	v_rcp_f32_e32 v52, v52
	s_nop 0
	v_fma_f32 v52, v52, -2.0, 2.0
	v_mul_f32_e32 v12, 0.5, v12
	v_mul_f32_e32 v12, v12, v52
	v_add_f32_e32 v13, v13, v53
	v_mul_f32_e32 v53, v13, v13
	v_mul_f32_e32 v53, v53, v13
	v_fmamk_f32 v53, v53, 0x3d372713, v13
	v_mul_f32_e32 v53, 0x40135761, v53
	v_exp_f32_e32 v53, v53
	s_nop 0
	v_add_f32_e32 v53, 1.0, v53
	v_rcp_f32_e32 v53, v53
	s_nop 0
	v_fma_f32 v53, v53, -2.0, 2.0
	v_mul_f32_e32 v13, 0.5, v13
	v_mul_f32_e32 v13, v13, v53
	v_add_f32_e32 v14, v14, v54
	v_mul_f32_e32 v54, v14, v14
	v_mul_f32_e32 v54, v54, v14
	v_fmamk_f32 v54, v54, 0x3d372713, v14
	v_mul_f32_e32 v54, 0x40135761, v54
	v_exp_f32_e32 v54, v54
	s_nop 0
	v_add_f32_e32 v54, 1.0, v54
	v_rcp_f32_e32 v54, v54
	s_nop 0
	v_fma_f32 v54, v54, -2.0, 2.0
	v_mul_f32_e32 v14, 0.5, v14
	v_mul_f32_e32 v14, v14, v54
	v_add_f32_e32 v15, v15, v55
	v_mul_f32_e32 v55, v15, v15
	v_mul_f32_e32 v55, v55, v15
	v_fmamk_f32 v55, v55, 0x3d372713, v15
	v_mul_f32_e32 v55, 0x40135761, v55
	v_exp_f32_e32 v55, v55
	s_nop 0
	v_add_f32_e32 v55, 1.0, v55
	v_rcp_f32_e32 v55, v55
	s_nop 0
	v_fma_f32 v55, v55, -2.0, 2.0
	v_mul_f32_e32 v15, 0.5, v15
	v_mul_f32_e32 v15, v15, v55
	v_add_f32_e32 v16, v16, v56
	v_mul_f32_e32 v56, v16, v16
	v_mul_f32_e32 v56, v56, v16
	v_fmamk_f32 v56, v56, 0x3d372713, v16
	v_mul_f32_e32 v56, 0x40135761, v56
	v_exp_f32_e32 v56, v56
	s_nop 0
	v_add_f32_e32 v56, 1.0, v56
	v_rcp_f32_e32 v56, v56
	s_nop 0
	v_fma_f32 v56, v56, -2.0, 2.0
	v_mul_f32_e32 v16, 0.5, v16
	v_mul_f32_e32 v16, v16, v56
	v_add_f32_e32 v17, v17, v57
	v_mul_f32_e32 v57, v17, v17
	v_mul_f32_e32 v57, v57, v17
	v_fmamk_f32 v57, v57, 0x3d372713, v17
	v_mul_f32_e32 v57, 0x40135761, v57
	v_exp_f32_e32 v57, v57
	s_nop 0
	v_add_f32_e32 v57, 1.0, v57
	v_rcp_f32_e32 v57, v57
	s_nop 0
	v_fma_f32 v57, v57, -2.0, 2.0
	v_mul_f32_e32 v17, 0.5, v17
	v_mul_f32_e32 v17, v17, v57
	v_add_f32_e32 v18, v18, v58
	v_mul_f32_e32 v58, v18, v18
	v_mul_f32_e32 v58, v58, v18
	v_fmamk_f32 v58, v58, 0x3d372713, v18
	v_mul_f32_e32 v58, 0x40135761, v58
	v_exp_f32_e32 v58, v58
	s_nop 0
	v_add_f32_e32 v58, 1.0, v58
	v_rcp_f32_e32 v58, v58
	s_nop 0
	v_fma_f32 v58, v58, -2.0, 2.0
	v_mul_f32_e32 v18, 0.5, v18
	v_mul_f32_e32 v18, v18, v58
	v_add_f32_e32 v19, v19, v59
	v_mul_f32_e32 v59, v19, v19
	v_mul_f32_e32 v59, v59, v19
	v_fmamk_f32 v59, v59, 0x3d372713, v19
	v_mul_f32_e32 v59, 0x40135761, v59
	v_exp_f32_e32 v59, v59
	s_nop 0
	v_add_f32_e32 v59, 1.0, v59
	v_rcp_f32_e32 v59, v59
	s_nop 0
	v_fma_f32 v59, v59, -2.0, 2.0
	v_mul_f32_e32 v19, 0.5, v19
	v_mul_f32_e32 v19, v19, v59
	v_add_f32_e32 v20, v20, v60
	v_mul_f32_e32 v60, v20, v20
	v_mul_f32_e32 v60, v60, v20
	v_fmamk_f32 v60, v60, 0x3d372713, v20
	v_mul_f32_e32 v60, 0x40135761, v60
	v_exp_f32_e32 v60, v60
	s_nop 0
	v_add_f32_e32 v60, 1.0, v60
	v_rcp_f32_e32 v60, v60
	s_nop 0
	v_fma_f32 v60, v60, -2.0, 2.0
	v_mul_f32_e32 v20, 0.5, v20
	v_mul_f32_e32 v20, v20, v60
	v_add_f32_e32 v21, v21, v61
	v_mul_f32_e32 v61, v21, v21
	v_mul_f32_e32 v61, v61, v21
	v_fmamk_f32 v61, v61, 0x3d372713, v21
	v_mul_f32_e32 v61, 0x40135761, v61
	v_exp_f32_e32 v61, v61
	s_nop 0
	v_add_f32_e32 v61, 1.0, v61
	v_rcp_f32_e32 v61, v61
	s_nop 0
	v_fma_f32 v61, v61, -2.0, 2.0
	v_mul_f32_e32 v21, 0.5, v21
	v_mul_f32_e32 v21, v21, v61
	v_add_f32_e32 v22, v22, v62
	v_mul_f32_e32 v62, v22, v22
	v_mul_f32_e32 v62, v62, v22
	v_fmamk_f32 v62, v62, 0x3d372713, v22
	v_mul_f32_e32 v62, 0x40135761, v62
	v_exp_f32_e32 v62, v62
	s_nop 0
	v_add_f32_e32 v62, 1.0, v62
	v_rcp_f32_e32 v62, v62
	s_nop 0
	v_fma_f32 v62, v62, -2.0, 2.0
	v_mul_f32_e32 v22, 0.5, v22
	v_mul_f32_e32 v22, v22, v62
	v_add_f32_e32 v23, v23, v63
	v_mul_f32_e32 v63, v23, v23
	v_mul_f32_e32 v63, v63, v23
	v_fmamk_f32 v63, v63, 0x3d372713, v23
	v_mul_f32_e32 v63, 0x40135761, v63
	v_exp_f32_e32 v63, v63
	s_nop 0
	v_add_f32_e32 v63, 1.0, v63
	v_rcp_f32_e32 v63, v63
	s_nop 0
	v_fma_f32 v63, v63, -2.0, 2.0
	v_mul_f32_e32 v23, 0.5, v23
	v_mul_f32_e32 v23, v23, v63
	v_add_f32_e32 v24, v24, v66
	v_mul_f32_e32 v66, v24, v24
	v_mul_f32_e32 v66, v66, v24
	v_fmamk_f32 v66, v66, 0x3d372713, v24
	v_mul_f32_e32 v66, 0x40135761, v66
	v_exp_f32_e32 v66, v66
	s_nop 0
	v_add_f32_e32 v66, 1.0, v66
	v_rcp_f32_e32 v66, v66
	s_nop 0
	v_fma_f32 v66, v66, -2.0, 2.0
	v_mul_f32_e32 v24, 0.5, v24
	v_mul_f32_e32 v24, v24, v66
	v_add_f32_e32 v25, v25, v67
	v_mul_f32_e32 v67, v25, v25
	v_mul_f32_e32 v67, v67, v25
	v_fmamk_f32 v67, v67, 0x3d372713, v25
	v_mul_f32_e32 v67, 0x40135761, v67
	v_exp_f32_e32 v67, v67
	s_nop 0
	v_add_f32_e32 v67, 1.0, v67
	v_rcp_f32_e32 v67, v67
	s_nop 0
	v_fma_f32 v67, v67, -2.0, 2.0
	v_mul_f32_e32 v25, 0.5, v25
	v_mul_f32_e32 v25, v25, v67
	v_add_f32_e32 v26, v26, v68
	v_mul_f32_e32 v68, v26, v26
	v_mul_f32_e32 v68, v68, v26
	v_fmamk_f32 v68, v68, 0x3d372713, v26
	v_mul_f32_e32 v68, 0x40135761, v68
	v_exp_f32_e32 v68, v68
	s_nop 0
	v_add_f32_e32 v68, 1.0, v68
	v_rcp_f32_e32 v68, v68
	s_nop 0
	v_fma_f32 v68, v68, -2.0, 2.0
	v_mul_f32_e32 v26, 0.5, v26
	v_mul_f32_e32 v26, v26, v68
	v_add_f32_e32 v27, v27, v69
	v_mul_f32_e32 v69, v27, v27
	v_mul_f32_e32 v69, v69, v27
	v_fmamk_f32 v69, v69, 0x3d372713, v27
	v_mul_f32_e32 v69, 0x40135761, v69
	v_exp_f32_e32 v69, v69
	s_nop 0
	v_add_f32_e32 v69, 1.0, v69
	v_rcp_f32_e32 v69, v69
	s_nop 0
	v_fma_f32 v69, v69, -2.0, 2.0
	v_mul_f32_e32 v27, 0.5, v27
	v_mul_f32_e32 v27, v27, v69
	v_add_f32_e32 v28, v28, v70
	v_mul_f32_e32 v70, v28, v28
	v_mul_f32_e32 v70, v70, v28
	v_fmamk_f32 v70, v70, 0x3d372713, v28
	v_mul_f32_e32 v70, 0x40135761, v70
	v_exp_f32_e32 v70, v70
	s_nop 0
	v_add_f32_e32 v70, 1.0, v70
	v_rcp_f32_e32 v70, v70
	s_nop 0
	v_fma_f32 v70, v70, -2.0, 2.0
	v_mul_f32_e32 v28, 0.5, v28
	v_mul_f32_e32 v28, v28, v70
	v_add_f32_e32 v29, v29, v71
	v_mul_f32_e32 v71, v29, v29
	v_mul_f32_e32 v71, v71, v29
	v_fmamk_f32 v71, v71, 0x3d372713, v29
	v_mul_f32_e32 v71, 0x40135761, v71
	v_exp_f32_e32 v71, v71
	s_nop 0
	v_add_f32_e32 v71, 1.0, v71
	v_rcp_f32_e32 v71, v71
	s_nop 0
	v_fma_f32 v71, v71, -2.0, 2.0
	v_mul_f32_e32 v29, 0.5, v29
	v_mul_f32_e32 v29, v29, v71
	v_add_f32_e32 v30, v30, v72
	v_mul_f32_e32 v72, v30, v30
	v_mul_f32_e32 v72, v72, v30
	v_fmamk_f32 v72, v72, 0x3d372713, v30
	v_mul_f32_e32 v72, 0x40135761, v72
	v_exp_f32_e32 v72, v72
	s_nop 0
	v_add_f32_e32 v72, 1.0, v72
	v_rcp_f32_e32 v72, v72
	s_nop 0
	v_fma_f32 v72, v72, -2.0, 2.0
	v_mul_f32_e32 v30, 0.5, v30
	v_mul_f32_e32 v30, v30, v72
	v_add_f32_e32 v31, v31, v73
	v_mul_f32_e32 v73, v31, v31
	v_mul_f32_e32 v73, v73, v31
	v_fmamk_f32 v73, v73, 0x3d372713, v31
	v_mul_f32_e32 v73, 0x40135761, v73
	v_exp_f32_e32 v73, v73
	s_nop 0
	v_add_f32_e32 v73, 1.0, v73
	v_rcp_f32_e32 v73, v73
	s_nop 0
	v_fma_f32 v73, v73, -2.0, 2.0
	v_mul_f32_e32 v31, 0.5, v31
	v_mul_f32_e32 v31, v31, v73
	v_cvt_pk_bf16_f32 v0, v0, v1
	v_cvt_pk_bf16_f32 v1, v2, v3
	v_cvt_pk_bf16_f32 v2, v4, v5
	v_cvt_pk_bf16_f32 v3, v6, v7
	v_cvt_pk_bf16_f32 v8, v8, v9
	v_cvt_pk_bf16_f32 v9, v10, v11
	v_cvt_pk_bf16_f32 v10, v12, v13
	v_cvt_pk_bf16_f32 v11, v14, v15
	v_cvt_pk_bf16_f32 v16, v16, v17
	v_cvt_pk_bf16_f32 v17, v18, v19
	v_cvt_pk_bf16_f32 v18, v20, v21
	v_cvt_pk_bf16_f32 v19, v22, v23
	v_cvt_pk_bf16_f32 v24, v24, v25
	v_cvt_pk_bf16_f32 v25, v26, v27
	v_cvt_pk_bf16_f32 v26, v28, v29
	v_cvt_pk_bf16_f32 v27, v30, v31
	v_mov_b32_e32 v4, 0
	v_mov_b32_e32 v5, 0
	v_mov_b32_e32 v6, 0
	v_mov_b32_e32 v7, 0
	v_mov_b32_e32 v12, 0
	v_mov_b32_e32 v13, 0
	v_mov_b32_e32 v14, 0
	v_mov_b32_e32 v15, 0
	v_mov_b32_e32 v20, 0
	v_mov_b32_e32 v21, 0
	v_mov_b32_e32 v22, 0
	v_mov_b32_e32 v23, 0
	v_mov_b32_e32 v28, 0
	v_mov_b32_e32 v29, 0
	v_mov_b32_e32 v30, 0
	v_mov_b32_e32 v31, 0
	global_load_dwordx2 v[40:41], v78, s[8:9] offset:0
	global_load_dwordx2 v[42:43], v78, s[8:9] offset:32
	global_load_dwordx2 v[44:45], v78, s[10:11] offset:0
	global_load_dwordx2 v[46:47], v78, s[10:11] offset:32
	global_load_dwordx2 v[48:49], v78, s[14:15] offset:0
	global_load_dwordx2 v[50:51], v78, s[14:15] offset:32
	global_load_dwordx2 v[52:53], v78, s[16:17] offset:0
	global_load_dwordx2 v[54:55], v78, s[16:17] offset:32
	global_load_dwordx2 v[56:57], v78, s[8:9] offset:64
	global_load_dwordx2 v[58:59], v78, s[8:9] offset:96
	global_load_dwordx2 v[60:61], v78, s[10:11] offset:64
	global_load_dwordx2 v[62:63], v78, s[10:11] offset:96
	global_load_dwordx2 v[66:67], v78, s[14:15] offset:64
	global_load_dwordx2 v[68:69], v78, s[14:15] offset:96
	global_load_dwordx2 v[70:71], v78, s[16:17] offset:64
	global_load_dwordx2 v[72:73], v78, s[16:17] offset:96
	s_waitcnt vmcnt(0)
	v_mfma_f32_16x16x32_bf16 v[4:7], v[40:43], v[0:3], v[4:7]
	v_mfma_f32_16x16x32_bf16 v[12:15], v[44:47], v[0:3], v[12:15]
	v_mfma_f32_16x16x32_bf16 v[20:23], v[48:51], v[0:3], v[20:23]
	v_mfma_f32_16x16x32_bf16 v[28:31], v[52:55], v[0:3], v[28:31]
	v_mfma_f32_16x16x32_bf16 v[4:7], v[56:59], v[8:11], v[4:7]
	v_mfma_f32_16x16x32_bf16 v[12:15], v[60:63], v[8:11], v[12:15]
	v_mfma_f32_16x16x32_bf16 v[20:23], v[66:69], v[8:11], v[20:23]
	v_mfma_f32_16x16x32_bf16 v[28:31], v[70:73], v[8:11], v[28:31]
	global_load_dwordx2 v[40:41], v78, s[8:9] offset:128
	global_load_dwordx2 v[42:43], v78, s[8:9] offset:160
	global_load_dwordx2 v[44:45], v78, s[10:11] offset:128
	global_load_dwordx2 v[46:47], v78, s[10:11] offset:160
	global_load_dwordx2 v[48:49], v78, s[14:15] offset:128
	global_load_dwordx2 v[50:51], v78, s[14:15] offset:160
	global_load_dwordx2 v[52:53], v78, s[16:17] offset:128
	global_load_dwordx2 v[54:55], v78, s[16:17] offset:160
	global_load_dwordx2 v[56:57], v78, s[8:9] offset:192
	global_load_dwordx2 v[58:59], v78, s[8:9] offset:224
	global_load_dwordx2 v[60:61], v78, s[10:11] offset:192
	global_load_dwordx2 v[62:63], v78, s[10:11] offset:224
	global_load_dwordx2 v[66:67], v78, s[14:15] offset:192
	global_load_dwordx2 v[68:69], v78, s[14:15] offset:224
	global_load_dwordx2 v[70:71], v78, s[16:17] offset:192
	global_load_dwordx2 v[72:73], v78, s[16:17] offset:224
	s_waitcnt vmcnt(0)
	v_mfma_f32_16x16x32_bf16 v[4:7], v[40:43], v[16:19], v[4:7]
	v_mfma_f32_16x16x32_bf16 v[12:15], v[44:47], v[16:19], v[12:15]
	v_mfma_f32_16x16x32_bf16 v[20:23], v[48:51], v[16:19], v[20:23]
	v_mfma_f32_16x16x32_bf16 v[28:31], v[52:55], v[16:19], v[28:31]
	v_mfma_f32_16x16x32_bf16 v[4:7], v[56:59], v[24:27], v[4:7]
	v_mfma_f32_16x16x32_bf16 v[12:15], v[60:63], v[24:27], v[12:15]
	v_mfma_f32_16x16x32_bf16 v[20:23], v[66:69], v[24:27], v[20:23]
	v_mfma_f32_16x16x32_bf16 v[28:31], v[70:73], v[24:27], v[28:31]
	s_nop 7
	s_nop 1
	s_and_b32 s18, s5, 63
	s_cmp_eq_u32 s2, 0
	s_cbranch_scc0 .Lcmpr_vstore
	s_lshl_b32 s0, s19, 17
	s_lshl_b32 s18, s18, 11
	s_add_i32 s0, s0, s18
	s_add_i32 s0, s0, 0x1e700000
	s_add_u32 s0, s26, s0
	s_addc_u32 s1, s27, 0
	v_lshlrev_b32_e32 v87, 4, v80
	v_lshrrev_b32_e32 v64, 1, v86
	v_lshl_add_u32 v87, v64, 8, v87
	v_and_b32_e32 v64, 1, v86
	v_lshl_add_u32 v87, v64, 3, v87
	v_cvt_pk_bf16_f32 v4, v4, v5
	v_cvt_pk_bf16_f32 v5, v6, v7
	global_store_dwordx2 v87, v[4:5], s[0:1] offset:0
	v_cvt_pk_bf16_f32 v12, v12, v13
	v_cvt_pk_bf16_f32 v13, v14, v15
	global_store_dwordx2 v87, v[12:13], s[0:1] offset:512
	v_cvt_pk_bf16_f32 v20, v20, v21
	v_cvt_pk_bf16_f32 v21, v22, v23
	global_store_dwordx2 v87, v[20:21], s[0:1] offset:1024
	v_cvt_pk_bf16_f32 v28, v28, v29
	v_cvt_pk_bf16_f32 v29, v30, v31
	global_store_dwordx2 v87, v[28:29], s[0:1] offset:1536
	s_branch .LBB0_399
.Lcmpr_vstore:
	s_lshl_b32 s0, s19, 17
	s_lshr_b32 s1, s18, 1
	s_lshl_b32 s1, s1, 12
	s_add_i32 s0, s0, s1
	s_and_b32 s1, s18, 1
	s_lshl_b32 s1, s1, 3
	s_add_i32 s0, s0, s1
	s_add_i32 s0, s0, 0x1e740000
	s_add_u32 s0, s26, s0
	s_addc_u32 s1, s27, 0
	v_lshrrev_b32_e32 v87, 2, v80
	v_lshlrev_b32_e32 v87, 8, v87
	v_lshl_add_u32 v87, v86, 6, v87
	v_and_b32_e32 v64, 3, v80
	v_lshl_add_u32 v87, v64, 1, v87
	v_cvt_pk_bf16_f32 v4, v4, v5
	v_cvt_pk_bf16_f32 v5, v6, v7
	global_store_short v87, v4, s[0:1] offset:0
	global_store_short_d16_hi v87, v4, s[0:1] offset:16
	global_store_short v87, v5, s[0:1] offset:32
	global_store_short_d16_hi v87, v5, s[0:1] offset:48
	v_cvt_pk_bf16_f32 v12, v12, v13
	v_cvt_pk_bf16_f32 v13, v14, v15
	global_store_short v87, v12, s[0:1] offset:1024
	global_store_short_d16_hi v87, v12, s[0:1] offset:1040
	global_store_short v87, v13, s[0:1] offset:1056
	global_store_short_d16_hi v87, v13, s[0:1] offset:1072
	v_cvt_pk_bf16_f32 v20, v20, v21
	v_cvt_pk_bf16_f32 v21, v22, v23
	global_store_short v87, v20, s[0:1] offset:2048
	global_store_short_d16_hi v87, v20, s[0:1] offset:2064
	global_store_short v87, v21, s[0:1] offset:2080
	global_store_short_d16_hi v87, v21, s[0:1] offset:2096
	v_cvt_pk_bf16_f32 v28, v28, v29
	v_cvt_pk_bf16_f32 v29, v30, v31
	global_store_short v87, v28, s[0:1] offset:3072
	global_store_short_d16_hi v87, v28, s[0:1] offset:3088
	global_store_short v87, v29, s[0:1] offset:3104
	global_store_short_d16_hi v87, v29, s[0:1] offset:3120
	s_branch .LBB0_399

.Lw_lut:
	v_max_i32_e32 v41, 0, v40
	v_min_i32_e32 v41, 0x3ff, v41
	v_cvt_f32_u32_e32 v42, v41
	v_mul_f32_e32 v42, 0x3d800000, v42
	v_log_f32_e32 v42, v42
	s_nop 0
	v_mul_f32_e32 v42, 0x40124925, v42
	v_cvt_i32_f32_e32 v42, v42
	v_med3_i32 v42, v42, 0, 15
	v_add_u32_e32 v42, 16, v42
	v_cmp_gt_u32_e32 vcc, 16, v41
	s_nop 1
	v_cndmask_b32_e32 v42, v42, v41, vcc
	v_lshl_add_u32 v42, v42, 4, s20
	v_lshl_add_u32 v42, v42, 2, s57
	ds_read_b32 v42, v42
	v_cmp_gt_u32_e32 vcc, 0x200, v40
	s_waitcnt lgkmcnt(0)
	v_mul_f32_e32 v42, 0x3fb8aa3b, v42
	v_cndmask_b32_e32 v42, v46, v42, vcc
	ds_write_b32 v47, v42
	v_add_u32_e32 v40, 64, v40
	v_add_u32_e32 v47, 0x100, v47
	s_add_i32 s0, s0, -1
	s_cmp_lg_u32 s0, 0
	s_cbranch_scc1 .Lw_lut
	s_waitcnt lgkmcnt(0)
	s_mov_b32 s6, 0
	s_lshl_b32 s8, s7, 4
	s_add_i32 s0, s8, 0xfffffe01
	s_max_i32 s0, s0, 0
	s_lshr_b32 s0, s0, 4
	s_and_b32 s11, s0, -2
	s_sub_i32 s0, s7, s11
	s_lshr_b32 s0, s0, 1
	s_add_i32 s9, s0, 1
	s_mov_b32 s10, 0
	s_mov_b32 s3, s7
	s_mov_b32 s29, s9
	s_mov_b32 s21, 0
	s_mov_b32 s38, 0
	s_lshl_b32 s0, s8, 11
	s_add_u32 s62, s34, s0
	s_addc_u32 s63, s35, 0
	v_lshlrev_b32_e32 v40, 11, v53
	v_lshl_add_u32 v40, v55, 1, v40
	v_add_u32_e32 v40, s39, v40
	global_load_dwordx4 v[16:19], v40, s[62:63]
	global_load_dwordx4 v[20:23], v40, s[62:63] offset:64
	s_lshl_b32 s0, s11, 4
	s_sub_i32 s0, s8, s0
	s_add_i32 s0, s0, 13
	s_lshl_b32 s0, s0, 2
	s_add_i32 s0, s0, s28
	v_sub_u32_e32 v50, v53, v54
	v_lshl_add_u32 v50, v50, 2, s0
	v_readfirstlane_b32 s1, v143
	s_and_b32 s0, s1, 3
	s_lshl_b32 s0, s0, 10
	s_cmp_lt_u32 s1, 4
	s_cselect_b32 s2, s12, s14
	s_cselect_b32 s16, s13, s15
	s_add_u32 s12, s2, s0
	s_addc_u32 s13, s16, 0
	s_lshl_b32 s23, s1, 10
	s_add_i32 s23, s23, 0x8000
	v_and_b32_e32 v96, 63, v208
	v_lshlrev_b32_e32 v96, 4, v96
	v_add_u32_e32 v97, 0x8000, v96
	s_barrier
	s_mov_b32 s18, 0
	s_mov_b32 s2, 0
	s_lshl_b32 s0, s2, 13
	s_add_i32 m0, s0, s23
	s_lshl_b32 s0, s11, 11
	s_add_u32 s16, s12, s0
	s_addc_u32 s17, s13, 0
	global_load_lds_dwordx4 v96, s[16:17]
	s_add_i32 s0, s21, 1
	s_cmp_lt_i32 s0, s29
	s_cbranch_scc1 .Lw_pfsamee1
	s_cmp_ge_i32 s38, 7
	s_cbranch_scc1 .Lw_pfgoe1
	s_add_i32 s38, s38, 1
	s_add_i32 s3, s3, 1
	s_lshl_b32 s1, s3, 4
	s_add_i32 s0, s1, 0xfffffe01
	s_max_i32 s0, s0, 0
	s_lshr_b32 s0, s0, 4
	s_and_b32 s11, s0, -2
	s_sub_i32 s0, s3, s11
	s_lshr_b32 s0, s0, 1
	s_add_i32 s29, s0, 1
	s_mov_b32 s21, 0
	s_branch .Lw_pfgoe1

.LBB0_559:
	s_or_b64 exec, exec, s[8:9]
	v_mov_b32_e32 v0, v208
	s_cmpk_gt_i32 s39, 0xff
	v_readfirstlane_b32 s0, v0
	s_cbranch_scc1 .LBB0_638
	s_ashr_i32 s40, s0, 6
	s_add_u32 s41, s20, 0x1e800000
	v_and_b32_e32 v79, 15, v0
	s_addc_u32 s48, s21, 0
	v_lshlrev_b32_e32 v64, 4, v79
	s_lshl_b32 s49, s40, 1
	v_and_b32_e32 v74, 63, v0
	v_bfe_u32 v5, v0, 4, 2
	v_lshl_add_u64 v[2:3], s[20:21], 0, v[64:65]
	v_and_b32_e32 v0, 48, v0
	v_lshlrev_b32_e32 v0, 4, v0
	v_mov_b32_e32 v1, v65
	s_add_u32 s22, s20, 0x1ad00000
	v_lshl_add_u64 v[2:3], v[2:3], 0, v[0:1]
	s_mov_b64 s[0:1], 0x1e700000
	s_addc_u32 s23, s21, 0
	v_lshl_add_u64 v[76:77], v[2:3], 0, s[0:1]
	s_add_u32 s24, s20, 0x1e500000
	s_mul_i32 s0, s40, 0x808
	s_addc_u32 s25, s21, 0
	s_add_i32 s0, s0, 0
	v_lshlrev_b32_e32 v1, 2, v74
	s_add_i32 s1, s0, 0x10100
	s_add_i32 s3, s0, 0x10504
	s_add_i32 s4, s0, 0x14140
	s_add_i32 s5, s0, 0x14544
	s_add_i32 s6, s0, 0x18180
	s_add_i32 s7, s0, 0x18584
	s_add_i32 s12, s0, 0x1c1c0
	s_add_i32 s13, s0, 0x1c5c4
	v_or_b32_e32 v80, 64, v74
	v_xor_b32_e32 v81, 64, v1
	v_xor_b32_e32 v100, 0x80, v1
	v_add_u32_e32 v2, 0xc0, v1
	v_add_u32_e32 v102, s0, v1
	v_add_u32_e32 v103, s1, v1
	v_add_u32_e32 v104, s3, v1
	v_add_u32_e32 v105, s4, v1
	v_add_u32_e32 v106, s5, v1
	v_add_u32_e32 v107, s6, v1
	v_add_u32_e32 v108, s7, v1
	v_add_u32_e32 v109, s12, v1
	v_add_u32_e32 v110, s13, v1
	v_or_b32_e32 v75, 0x80, v74
	v_lshlrev_b32_e32 v1, 2, v80
	v_add_u32_e32 v111, s0, v1
	v_add_u32_e32 v112, s1, v1
	v_add_u32_e32 v113, s3, v1
	v_add_u32_e32 v114, s4, v1
	v_add_u32_e32 v115, s5, v1
	v_add_u32_e32 v116, s6, v1
	v_add_u32_e32 v117, s7, v1
	v_add_u32_e32 v118, s12, v1
	v_add_u32_e32 v119, s13, v1
	v_lshlrev_b32_e32 v1, 2, v75
	v_or_b32_e32 v129, 0xc0, v74
	s_mul_i32 s2, s40, 0x4040
	v_add_u32_e32 v120, s0, v1
	v_add_u32_e32 v121, s1, v1
	v_add_u32_e32 v122, s3, v1
	v_add_u32_e32 v123, s4, v1
	v_add_u32_e32 v124, s5, v1
	v_add_u32_e32 v125, s6, v1
	v_add_u32_e32 v126, s7, v1
	v_add_u32_e32 v127, s12, v1
	v_add_u32_e32 v128, s13, v1
	v_lshlrev_b32_e32 v1, 2, v129
	v_add_u32_e32 v130, s1, v1
	v_add_u32_e32 v131, s3, v1
	v_add_u32_e32 v132, s4, v1
	v_add_u32_e32 v133, s5, v1
	v_add_u32_e32 v134, s6, v1
	v_add_u32_e32 v135, s7, v1
	v_add_u32_e32 v136, s12, v1
	v_add_u32_e32 v137, s13, v1
	v_lshlrev_b32_e32 v1, 6, v5
	s_add_i32 s0, s2, 0
	v_sub_u32_e32 v139, v79, v1
	v_mov_b32_e32 v1, s0
	s_movk_i32 s0, 0x404
	v_or_b32_e32 v64, v64, v0
	v_lshlrev_b32_e32 v4, 3, v5
	v_lshlrev_b32_e32 v78, 2, v5
	v_mad_u32_u24 v140, v79, s0, v1
	v_lshl_add_u64 v[0:1], s[20:21], 0, v[64:65]
	s_mov_b64 s[0:1], 0x1e740000
	v_and_b32_e32 v101, 0xfc, v2
	v_cmp_gt_u32_e64 s[8:9], 16, v74
	v_cmp_ne_u32_e64 s[10:11], 0, v74
	v_cmp_eq_u32_e64 s[12:13], 0, v74
	v_or_b32_e32 v138, 19, v78
	v_lshl_add_u64 v[82:83], v[0:1], 0, s[0:1]
	v_lshlrev_b32_e32 v84, 1, v4
	v_lshlrev_b32_e32 v86, 1, v78
	s_branch .LBB0_562

.LBB0_630:
	s_mov_b32 m0, s2
	v_cmp_gt_f32_e64 s[4:5], v0, v8
	v_cmp_gt_f32_e64 s[6:7], v2, v10
	s_nop 0
	v_cndmask_b32_e64 v12, v8, v0, s[4:5]
	v_cndmask_b32_e64 v14, v74, v80, s[4:5]
	v_cndmask_b32_e64 v13, v10, v2, s[6:7]
	v_cndmask_b32_e64 v15, v74, v80, s[6:7]
	v_cmp_gt_f32_e64 s[4:5], v1, v12
	v_cmp_gt_f32_e64 s[6:7], v3, v13
	s_nop 0
	v_cndmask_b32_e64 v12, v12, v1, s[4:5]
	v_cndmask_b32_e64 v14, v14, v75, s[4:5]
	v_cndmask_b32_e64 v13, v13, v3, s[6:7]
	v_cndmask_b32_e64 v15, v15, v75, s[6:7]
	v_cmp_gt_f32_e64 s[4:5], v9, v12
	v_cmp_gt_f32_e64 s[6:7], v11, v13
	s_nop 0
	v_cndmask_b32_e64 v12, v12, v9, s[4:5]
	v_cndmask_b32_e64 v14, v14, v129, s[4:5]
	v_cndmask_b32_e64 v13, v13, v11, s[6:7]
	v_cndmask_b32_e64 v15, v15, v129, s[6:7]
	v_mov_b32_e32 v16, v12
	v_mov_b32_e32 v17, v13
	s_nop 1
	v_max_f32_dpp v16, v16, v16 quad_perm:[1,0,3,2] row_mask:0xf bank_mask:0xf
	v_max_f32_dpp v17, v17, v17 quad_perm:[1,0,3,2] row_mask:0xf bank_mask:0xf
	s_nop 0
	v_max_f32_dpp v16, v16, v16 quad_perm:[2,3,0,1] row_mask:0xf bank_mask:0xf
	v_max_f32_dpp v17, v17, v17 quad_perm:[2,3,0,1] row_mask:0xf bank_mask:0xf
	s_nop 0
	v_max_f32_dpp v16, v16, v16 row_ror:4 row_mask:0xf bank_mask:0xf
	v_max_f32_dpp v17, v17, v17 row_ror:4 row_mask:0xf bank_mask:0xf
	s_nop 0
	v_max_f32_dpp v16, v16, v16 row_ror:8 row_mask:0xf bank_mask:0xf
	v_max_f32_dpp v17, v17, v17 row_ror:8 row_mask:0xf bank_mask:0xf
	s_nop 0
	v_readlane_b32 s4, v16, 0
	v_readlane_b32 s5, v16, 16
	v_readlane_b32 s6, v16, 32
	v_readlane_b32 s7, v16, 48
	v_readlane_b32 s14, v17, 0
	v_readlane_b32 s15, v17, 16
	v_readlane_b32 s16, v17, 32
	v_readlane_b32 s17, v17, 48
	s_max_i32 s4, s4, s5
	s_max_i32 s6, s6, s7
	s_max_i32 s4, s4, s6
	s_max_i32 s14, s14, s15
	s_max_i32 s16, s16, s17
	s_max_i32 s14, s14, s16
	v_cmp_eq_f32_e64 s[6:7], s4, v12
	v_cmp_eq_f32_e64 s[16:17], s14, v13
	s_ff1_i32_b64 s5, s[6:7]
	s_ff1_i32_b64 s15, s[16:17]
	v_readlane_b32 s6, v14, s5
	v_readlane_b32 s7, v15, s15
	s_nop 1
	v_writelane_b32 v20, s6, m0
	v_writelane_b32 v21, s7, m0
	v_cmp_ne_u32_e64 vcc, s6, v74
	v_cmp_ne_u32_e64 s[4:5], s6, v80
	v_cmp_ne_u32_e64 s[14:15], s6, v75
	v_cmp_ne_u32_e64 s[16:17], s6, v129
	v_cndmask_b32_e64 v8, -2.0, v8, vcc
	v_cndmask_b32_e64 v0, -2.0, v0, s[4:5]
	v_cndmask_b32_e64 v1, -2.0, v1, s[14:15]
	v_cndmask_b32_e64 v9, -2.0, v9, s[16:17]
	v_cmp_ne_u32_e64 vcc, s7, v74
	v_cmp_ne_u32_e64 s[4:5], s7, v80
	v_cmp_ne_u32_e64 s[14:15], s7, v75
	v_cmp_ne_u32_e64 s[16:17], s7, v129
	v_cndmask_b32_e64 v10, -2.0, v10, vcc
	v_cndmask_b32_e64 v2, -2.0, v2, s[4:5]
	v_cndmask_b32_e64 v3, -2.0, v3, s[14:15]
	v_cndmask_b32_e64 v11, -2.0, v11, s[16:17]
	s_add_i32 s2, s2, 1
	s_cmp_lg_u32 s2, 13
	s_cbranch_scc1 .LBB0_630
	v_readfirstlane_b32 s14, v4
	v_readfirstlane_b32 s15, v5
	s_add_u32 s14, s14, 0x1e800000
	s_addc_u32 s15, s15, 0
	v_lshlrev_b32_e32 v22, 2, v74
	v_cmp_gt_u32_e64 s[4:5], 13, v74
	s_and_saveexec_b64 s[6:7], s[4:5]
	global_store_dword v22, v20, s[14:15] offset:12
	global_store_dword v22, v21, s[14:15] offset:140
	s_mov_b64 exec, s[6:7]
